# gate/up (SwiGLU) epilogue re-emitted stage by stage in place in the accumulators: no dependent chains, nops or moves (epilogue 32 -> 21 us per workgroup)
# speedup vs baseline: 1.0111x; 1.0111x over previous
.LBB0_1542:
	v_lshl_add_u32 v140, s11, 8, v146
	v_ashrrev_i32_e32 v141, 31, v140
	v_lshl_add_u64 v[142:143], v[140:141], 2, s[46:47]
	v_mov_b32_e32 v144, v244
	v_mov_b32_e32 v162, v245
	v_mov_b32_e32 v160, v246
	v_mov_b32_e32 v158, v247
	v_mov_b32_e32 v156, v248
	v_mov_b32_e32 v154, v249
	v_mov_b32_e32 v152, v250
	v_mov_b32_e32 v150, v251
	v_mov_b32_e32 v164, v122
	v_mov_b32_e32 v165, v126
	v_lshl_or_b32 v142, s8, 7, v148
	v_ashrrev_i32_e32 v143, 31, v142
	s_movk_i32 s6, 0x2c00
	v_or_b32_e32 v161, 16, v140
	v_or_b32_e32 v159, 32, v140
	v_or_b32_e32 v157, 48, v140
	v_add_u32_e32 v155, 0x80, v140
	v_add_u32_e32 v153, 0x90, v140
	v_add_u32_e32 v151, 0xa0, v140
	v_add_u32_e32 v141, 0xb0, v140
	s_waitcnt vmcnt(8) lgkmcnt(0)
	v_fmamk_f32 v144, v144, 0x3a000000, v224
	v_cmp_gt_f32_e32 vcc, s19, v144
	v_mul_f32_e32 v163, 0x4b800000, v144
	s_nop 0
	v_cndmask_b32_e32 v144, v144, v163, vcc
	v_rsq_f32_e32 v144, v144
	s_nop 0
	v_mul_f32_e32 v163, 0x45800000, v144
	v_cndmask_b32_e32 v144, v144, v163, vcc
	v_pk_mul_f32 v[122:123], v[122:123], v[144:145] op_sel_hi:[1,0]
	v_pk_mul_f32 v[124:125], v[124:125], v[144:145] op_sel_hi:[1,0]
	v_pk_mul_f32 v[126:127], v[126:127], v[144:145] op_sel_hi:[1,0]
	v_pk_mul_f32 v[128:129], v[128:129], v[144:145] op_sel_hi:[1,0]
	v_pk_mul_f32 v[114:115], v[114:115], v[144:145] op_sel_hi:[1,0]
	v_pk_mul_f32 v[116:117], v[116:117], v[144:145] op_sel_hi:[1,0]
	v_pk_mul_f32 v[118:119], v[118:119], v[144:145] op_sel_hi:[1,0]
	v_pk_mul_f32 v[120:121], v[120:121], v[144:145] op_sel_hi:[1,0]
	v_mul_f32_e32 v163, 0xbfb8aa3b, v126
	v_mul_f32_e32 v164, 0xbfb8aa3b, v127
	v_mul_f32_e32 v165, 0xbfb8aa3b, v128
	v_exp_f32_e32 v163, v163
	v_exp_f32_e32 v164, v164
	v_exp_f32_e32 v165, v165
	v_add_f32_e32 v163, 1.0, v163
	v_add_f32_e32 v164, 1.0, v164
	v_add_f32_e32 v165, 1.0, v165
	v_rcp_f32_e32 v163, v163
	v_rcp_f32_e32 v164, v164
	v_rcp_f32_e32 v165, v165
	v_mul_f32_e32 v126, v126, v163
	v_mul_f32_e32 v127, v127, v164
	v_mul_f32_e32 v128, v128, v165
	v_mul_f32_e32 v122, v122, v126
	v_mul_f32_e32 v123, v123, v127
	v_mul_f32_e32 v124, v124, v128
	v_mul_f32_e32 v126, 0xbfb8aa3b, v129
	v_mul_f32_e32 v127, 0xbfb8aa3b, v118
	v_mul_f32_e32 v128, 0xbfb8aa3b, v119
	v_mul_f32_e32 v163, 0xbfb8aa3b, v120
	v_mul_f32_e32 v164, 0xbfb8aa3b, v121
	v_exp_f32_e32 v126, v126
	v_exp_f32_e32 v127, v127
	v_exp_f32_e32 v128, v128
	v_exp_f32_e32 v163, v163
	v_exp_f32_e32 v164, v164
	v_add_f32_e32 v126, 1.0, v126
	v_add_f32_e32 v127, 1.0, v127
	v_add_f32_e32 v128, 1.0, v128
	v_add_f32_e32 v163, 1.0, v163
	v_add_f32_e32 v164, 1.0, v164
	v_rcp_f32_e32 v126, v126
	v_rcp_f32_e32 v127, v127
	v_rcp_f32_e32 v128, v128
	v_rcp_f32_e32 v163, v163
	v_rcp_f32_e32 v164, v164
	v_mul_f32_e32 v129, v129, v126
	v_mul_f32_e32 v118, v118, v127
	v_mul_f32_e32 v119, v119, v128
	v_mul_f32_e32 v120, v120, v163
	v_mul_f32_e32 v121, v121, v164
	v_mul_f32_e32 v125, v125, v129
	v_mul_f32_e32 v114, v114, v118
	v_mul_f32_e32 v115, v115, v119
	v_mul_f32_e32 v116, v116, v120
	v_mul_f32_e32 v117, v117, v121
	v_cvt_pk_bf16_f32 v118, v122, v123
	v_cvt_pk_bf16_f32 v119, v124, v125
	v_cvt_pk_bf16_f32 v120, v114, v115
	v_cvt_pk_bf16_f32 v121, v116, v117
	v_mov_b64_e32 v[114:115], s[44:45]
	v_mad_i64_i32 v[126:127], s[4:5], v140, s6, v[114:115]
	v_lshlrev_b64 v[116:117], 1, v[142:143]
	v_lshl_add_u64 v[126:127], v[126:127], 0, v[116:117]
	flat_store_dwordx4 v[126:127], v[118:121] nt
	s_nop 1
	v_fmamk_f32 v118, v162, 0x3a000000, v224
	v_cmp_gt_f32_e32 vcc, s19, v118
	v_mul_f32_e32 v119, 0x4b800000, v118
	s_nop 0
	v_cndmask_b32_e32 v118, v118, v119, vcc
	v_rsq_f32_e32 v118, v118
	s_nop 0
	v_mul_f32_e32 v119, 0x45800000, v118
	v_cndmask_b32_e32 v118, v118, v119, vcc
	v_pk_mul_f32 v[106:107], v[106:107], v[118:119] op_sel_hi:[1,0]
	v_pk_mul_f32 v[108:109], v[108:109], v[118:119] op_sel_hi:[1,0]
	v_pk_mul_f32 v[110:111], v[110:111], v[118:119] op_sel_hi:[1,0]
	v_pk_mul_f32 v[112:113], v[112:113], v[118:119] op_sel_hi:[1,0]
	v_pk_mul_f32 v[98:99], v[98:99], v[118:119] op_sel_hi:[1,0]
	v_pk_mul_f32 v[100:101], v[100:101], v[118:119] op_sel_hi:[1,0]
	v_pk_mul_f32 v[102:103], v[102:103], v[118:119] op_sel_hi:[1,0]
	v_pk_mul_f32 v[104:105], v[104:105], v[118:119] op_sel_hi:[1,0]
	v_mul_f32_e32 v122, 0xbfb8aa3b, v110
	v_mul_f32_e32 v123, 0xbfb8aa3b, v111
	v_mul_f32_e32 v124, 0xbfb8aa3b, v112
	v_mul_f32_e32 v125, 0xbfb8aa3b, v113
	v_exp_f32_e32 v122, v122
	v_exp_f32_e32 v123, v123
	v_exp_f32_e32 v124, v124
	v_exp_f32_e32 v125, v125
	v_add_f32_e32 v122, 1.0, v122
	v_add_f32_e32 v123, 1.0, v123
	v_add_f32_e32 v124, 1.0, v124
	v_add_f32_e32 v125, 1.0, v125
	v_rcp_f32_e32 v122, v122
	v_rcp_f32_e32 v123, v123
	v_rcp_f32_e32 v124, v124
	v_rcp_f32_e32 v125, v125
	v_mul_f32_e32 v110, v110, v122
	v_mul_f32_e32 v111, v111, v123
	v_mul_f32_e32 v112, v112, v124
	v_mul_f32_e32 v113, v113, v125
	v_mul_f32_e32 v106, v106, v110
	v_mul_f32_e32 v107, v107, v111
	v_mul_f32_e32 v108, v108, v112
	v_mul_f32_e32 v109, v109, v113
	v_mul_f32_e32 v110, 0xbfb8aa3b, v102
	v_mul_f32_e32 v111, 0xbfb8aa3b, v103
	v_mul_f32_e32 v112, 0xbfb8aa3b, v104
	v_mul_f32_e32 v113, 0xbfb8aa3b, v105
	v_exp_f32_e32 v110, v110
	v_exp_f32_e32 v111, v111
	v_exp_f32_e32 v112, v112
	v_exp_f32_e32 v113, v113
	v_add_f32_e32 v110, 1.0, v110
	v_add_f32_e32 v111, 1.0, v111
	v_add_f32_e32 v112, 1.0, v112
	v_add_f32_e32 v113, 1.0, v113
	v_rcp_f32_e32 v110, v110
	v_rcp_f32_e32 v111, v111
	v_rcp_f32_e32 v112, v112
	v_rcp_f32_e32 v113, v113
	v_mul_f32_e32 v102, v102, v110
	v_mul_f32_e32 v103, v103, v111
	v_mul_f32_e32 v104, v104, v112
	v_mul_f32_e32 v105, v105, v113
	v_mul_f32_e32 v98, v98, v102
	v_mul_f32_e32 v99, v99, v103
	v_mul_f32_e32 v100, v100, v104
	v_mul_f32_e32 v101, v101, v105
	v_cvt_pk_bf16_f32 v102, v106, v107
	v_cvt_pk_bf16_f32 v103, v108, v109
	v_cvt_pk_bf16_f32 v104, v98, v99
	v_cvt_pk_bf16_f32 v105, v100, v101
	v_mad_i64_i32 v[110:111], s[4:5], v161, s6, v[114:115]
	v_lshl_add_u64 v[110:111], v[110:111], 0, v[116:117]
	flat_store_dwordx4 v[110:111], v[102:105] nt
	s_nop 1
	v_fmamk_f32 v98, v160, 0x3a000000, v224
	v_cmp_gt_f32_e32 vcc, s19, v98
	v_mul_f32_e32 v99, 0x4b800000, v98
	s_nop 0
	v_cndmask_b32_e32 v98, v98, v99, vcc
	v_rsq_f32_e32 v98, v98
	s_nop 0
	v_mul_f32_e32 v99, 0x45800000, v98
	v_cndmask_b32_e32 v98, v98, v99, vcc
	v_pk_mul_f32 v[90:91], v[90:91], v[98:99] op_sel_hi:[1,0]
	v_pk_mul_f32 v[92:93], v[92:93], v[98:99] op_sel_hi:[1,0]
	v_pk_mul_f32 v[94:95], v[94:95], v[98:99] op_sel_hi:[1,0]
	v_pk_mul_f32 v[96:97], v[96:97], v[98:99] op_sel_hi:[1,0]
	v_pk_mul_f32 v[82:83], v[82:83], v[98:99] op_sel_hi:[1,0]
	v_pk_mul_f32 v[84:85], v[84:85], v[98:99] op_sel_hi:[1,0]
	v_pk_mul_f32 v[86:87], v[86:87], v[98:99] op_sel_hi:[1,0]
	v_pk_mul_f32 v[88:89], v[88:89], v[98:99] op_sel_hi:[1,0]
	v_mul_f32_e32 v106, 0xbfb8aa3b, v94
	v_mul_f32_e32 v107, 0xbfb8aa3b, v95
	v_mul_f32_e32 v108, 0xbfb8aa3b, v96
	v_mul_f32_e32 v109, 0xbfb8aa3b, v97
	v_exp_f32_e32 v106, v106
	v_exp_f32_e32 v107, v107
	v_exp_f32_e32 v108, v108
	v_exp_f32_e32 v109, v109
	v_add_f32_e32 v106, 1.0, v106
	v_add_f32_e32 v107, 1.0, v107
	v_add_f32_e32 v108, 1.0, v108
	v_add_f32_e32 v109, 1.0, v109
	v_rcp_f32_e32 v106, v106
	v_rcp_f32_e32 v107, v107
	v_rcp_f32_e32 v108, v108
	v_rcp_f32_e32 v109, v109
	v_mul_f32_e32 v94, v94, v106
	v_mul_f32_e32 v95, v95, v107
	v_mul_f32_e32 v96, v96, v108
	v_mul_f32_e32 v97, v97, v109
	v_mul_f32_e32 v90, v90, v94
	v_mul_f32_e32 v91, v91, v95
	v_mul_f32_e32 v92, v92, v96
	v_mul_f32_e32 v93, v93, v97
	v_mul_f32_e32 v94, 0xbfb8aa3b, v86
	v_mul_f32_e32 v95, 0xbfb8aa3b, v87
	v_mul_f32_e32 v96, 0xbfb8aa3b, v88
	v_mul_f32_e32 v97, 0xbfb8aa3b, v89
	v_exp_f32_e32 v94, v94
	v_exp_f32_e32 v95, v95
	v_exp_f32_e32 v96, v96
	v_exp_f32_e32 v97, v97
	v_add_f32_e32 v94, 1.0, v94
	v_add_f32_e32 v95, 1.0, v95
	v_add_f32_e32 v96, 1.0, v96
	v_add_f32_e32 v97, 1.0, v97
	v_rcp_f32_e32 v94, v94
	v_rcp_f32_e32 v95, v95
	v_rcp_f32_e32 v96, v96
	v_rcp_f32_e32 v97, v97
	v_mul_f32_e32 v86, v86, v94
	v_mul_f32_e32 v87, v87, v95
	v_mul_f32_e32 v88, v88, v96
	v_mul_f32_e32 v89, v89, v97
	v_mul_f32_e32 v82, v82, v86
	v_mul_f32_e32 v83, v83, v87
	v_mul_f32_e32 v84, v84, v88
	v_mul_f32_e32 v85, v85, v89
	v_cvt_pk_bf16_f32 v86, v90, v91
	v_cvt_pk_bf16_f32 v87, v92, v93
	v_cvt_pk_bf16_f32 v88, v82, v83
	v_cvt_pk_bf16_f32 v89, v84, v85
	v_mad_i64_i32 v[94:95], s[4:5], v159, s6, v[114:115]
	v_lshl_add_u64 v[94:95], v[94:95], 0, v[116:117]
	flat_store_dwordx4 v[94:95], v[86:89] nt
	s_nop 1
	v_fmamk_f32 v82, v158, 0x3a000000, v224
	v_cmp_gt_f32_e32 vcc, s19, v82
	v_mul_f32_e32 v83, 0x4b800000, v82
	s_nop 0
	v_cndmask_b32_e32 v82, v82, v83, vcc
	v_rsq_f32_e32 v82, v82
	s_nop 0
	v_mul_f32_e32 v83, 0x45800000, v82
	v_cndmask_b32_e32 v82, v82, v83, vcc
	v_pk_mul_f32 v[74:75], v[74:75], v[82:83] op_sel_hi:[1,0]
	v_pk_mul_f32 v[76:77], v[76:77], v[82:83] op_sel_hi:[1,0]
	v_pk_mul_f32 v[78:79], v[78:79], v[82:83] op_sel_hi:[1,0]
	v_pk_mul_f32 v[80:81], v[80:81], v[82:83] op_sel_hi:[1,0]
	v_pk_mul_f32 v[66:67], v[66:67], v[82:83] op_sel_hi:[1,0]
	v_pk_mul_f32 v[68:69], v[68:69], v[82:83] op_sel_hi:[1,0]
	v_pk_mul_f32 v[70:71], v[70:71], v[82:83] op_sel_hi:[1,0]
	v_pk_mul_f32 v[72:73], v[72:73], v[82:83] op_sel_hi:[1,0]
	v_mul_f32_e32 v90, 0xbfb8aa3b, v78
	v_mul_f32_e32 v91, 0xbfb8aa3b, v79
	v_mul_f32_e32 v92, 0xbfb8aa3b, v80
	v_mul_f32_e32 v93, 0xbfb8aa3b, v81
	v_exp_f32_e32 v90, v90
	v_exp_f32_e32 v91, v91
	v_exp_f32_e32 v92, v92
	v_exp_f32_e32 v93, v93
	v_add_f32_e32 v90, 1.0, v90
	v_add_f32_e32 v91, 1.0, v91
	v_add_f32_e32 v92, 1.0, v92
	v_add_f32_e32 v93, 1.0, v93
	v_rcp_f32_e32 v90, v90
	v_rcp_f32_e32 v91, v91
	v_rcp_f32_e32 v92, v92
	v_rcp_f32_e32 v93, v93
	v_mul_f32_e32 v78, v78, v90
	v_mul_f32_e32 v79, v79, v91
	v_mul_f32_e32 v80, v80, v92
	v_mul_f32_e32 v81, v81, v93
	v_mul_f32_e32 v74, v74, v78
	v_mul_f32_e32 v75, v75, v79
	v_mul_f32_e32 v76, v76, v80
	v_mul_f32_e32 v77, v77, v81
	v_mul_f32_e32 v78, 0xbfb8aa3b, v70
	v_mul_f32_e32 v79, 0xbfb8aa3b, v71
	v_mul_f32_e32 v80, 0xbfb8aa3b, v72
	v_mul_f32_e32 v81, 0xbfb8aa3b, v73
	v_exp_f32_e32 v78, v78
	v_exp_f32_e32 v79, v79
	v_exp_f32_e32 v80, v80
	v_exp_f32_e32 v81, v81
	v_add_f32_e32 v78, 1.0, v78
	v_add_f32_e32 v79, 1.0, v79
	v_add_f32_e32 v80, 1.0, v80
	v_add_f32_e32 v81, 1.0, v81
	v_rcp_f32_e32 v78, v78
	v_rcp_f32_e32 v79, v79
	v_rcp_f32_e32 v80, v80
	v_rcp_f32_e32 v81, v81
	v_mul_f32_e32 v70, v70, v78
	v_mul_f32_e32 v71, v71, v79
	v_mul_f32_e32 v72, v72, v80
	v_mul_f32_e32 v73, v73, v81
	v_mul_f32_e32 v66, v66, v70
	v_mul_f32_e32 v67, v67, v71
	v_mul_f32_e32 v68, v68, v72
	v_mul_f32_e32 v69, v69, v73
	v_cvt_pk_bf16_f32 v70, v74, v75
	v_cvt_pk_bf16_f32 v71, v76, v77
	v_cvt_pk_bf16_f32 v72, v66, v67
	v_cvt_pk_bf16_f32 v73, v68, v69
	v_mad_i64_i32 v[78:79], s[4:5], v157, s6, v[114:115]
	v_lshl_add_u64 v[78:79], v[78:79], 0, v[116:117]
	flat_store_dwordx4 v[78:79], v[70:73] nt
	s_nop 1
	v_fmamk_f32 v66, v156, 0x3a000000, v224
	v_cmp_gt_f32_e32 vcc, s19, v66
	v_mul_f32_e32 v67, 0x4b800000, v66
	s_nop 0
	v_cndmask_b32_e32 v66, v66, v67, vcc
	v_rsq_f32_e32 v66, v66
	s_nop 0
	v_mul_f32_e32 v67, 0x45800000, v66
	v_cndmask_b32_e32 v66, v66, v67, vcc
	v_pk_mul_f32 v[58:59], v[58:59], v[66:67] op_sel_hi:[1,0]
	v_pk_mul_f32 v[60:61], v[60:61], v[66:67] op_sel_hi:[1,0]
	v_pk_mul_f32 v[62:63], v[62:63], v[66:67] op_sel_hi:[1,0]
	v_pk_mul_f32 v[64:65], v[64:65], v[66:67] op_sel_hi:[1,0]
	v_pk_mul_f32 v[50:51], v[50:51], v[66:67] op_sel_hi:[1,0]
	v_pk_mul_f32 v[52:53], v[52:53], v[66:67] op_sel_hi:[1,0]
	v_pk_mul_f32 v[54:55], v[54:55], v[66:67] op_sel_hi:[1,0]
	v_pk_mul_f32 v[56:57], v[56:57], v[66:67] op_sel_hi:[1,0]
	v_mul_f32_e32 v74, 0xbfb8aa3b, v62
	v_mul_f32_e32 v75, 0xbfb8aa3b, v63
	v_mul_f32_e32 v76, 0xbfb8aa3b, v64
	v_mul_f32_e32 v77, 0xbfb8aa3b, v65
	v_exp_f32_e32 v74, v74
	v_exp_f32_e32 v75, v75
	v_exp_f32_e32 v76, v76
	v_exp_f32_e32 v77, v77
	v_add_f32_e32 v74, 1.0, v74
	v_add_f32_e32 v75, 1.0, v75
	v_add_f32_e32 v76, 1.0, v76
	v_add_f32_e32 v77, 1.0, v77
	v_rcp_f32_e32 v74, v74
	v_rcp_f32_e32 v75, v75
	v_rcp_f32_e32 v76, v76
	v_rcp_f32_e32 v77, v77
	v_mul_f32_e32 v62, v62, v74
	v_mul_f32_e32 v63, v63, v75
	v_mul_f32_e32 v64, v64, v76
	v_mul_f32_e32 v65, v65, v77
	v_mul_f32_e32 v58, v58, v62
	v_mul_f32_e32 v59, v59, v63
	v_mul_f32_e32 v60, v60, v64
	v_mul_f32_e32 v61, v61, v65
	v_mul_f32_e32 v62, 0xbfb8aa3b, v54
	v_mul_f32_e32 v63, 0xbfb8aa3b, v55
	v_mul_f32_e32 v64, 0xbfb8aa3b, v56
	v_mul_f32_e32 v65, 0xbfb8aa3b, v57
	v_exp_f32_e32 v62, v62
	v_exp_f32_e32 v63, v63
	v_exp_f32_e32 v64, v64
	v_exp_f32_e32 v65, v65
	v_add_f32_e32 v62, 1.0, v62
	v_add_f32_e32 v63, 1.0, v63
	v_add_f32_e32 v64, 1.0, v64
	v_add_f32_e32 v65, 1.0, v65
	v_rcp_f32_e32 v62, v62
	v_rcp_f32_e32 v63, v63
	v_rcp_f32_e32 v64, v64
	v_rcp_f32_e32 v65, v65
	v_mul_f32_e32 v54, v54, v62
	v_mul_f32_e32 v55, v55, v63
	v_mul_f32_e32 v56, v56, v64
	v_mul_f32_e32 v57, v57, v65
	v_mul_f32_e32 v50, v50, v54
	v_mul_f32_e32 v51, v51, v55
	v_mul_f32_e32 v52, v52, v56
	v_mul_f32_e32 v53, v53, v57
	v_cvt_pk_bf16_f32 v54, v58, v59
	v_cvt_pk_bf16_f32 v55, v60, v61
	v_cvt_pk_bf16_f32 v56, v50, v51
	v_cvt_pk_bf16_f32 v57, v52, v53
	v_mad_i64_i32 v[62:63], s[4:5], v155, s6, v[114:115]
	v_lshl_add_u64 v[62:63], v[62:63], 0, v[116:117]
	flat_store_dwordx4 v[62:63], v[54:57] nt
	s_nop 1
	v_fmamk_f32 v50, v154, 0x3a000000, v224
	v_cmp_gt_f32_e32 vcc, s19, v50
	v_mul_f32_e32 v51, 0x4b800000, v50
	s_nop 0
	v_cndmask_b32_e32 v50, v50, v51, vcc
	v_rsq_f32_e32 v50, v50
	s_nop 0
	v_mul_f32_e32 v51, 0x45800000, v50
	v_cndmask_b32_e32 v50, v50, v51, vcc
	v_pk_mul_f32 v[42:43], v[42:43], v[50:51] op_sel_hi:[1,0]
	v_pk_mul_f32 v[44:45], v[44:45], v[50:51] op_sel_hi:[1,0]
	v_pk_mul_f32 v[46:47], v[46:47], v[50:51] op_sel_hi:[1,0]
	v_pk_mul_f32 v[48:49], v[48:49], v[50:51] op_sel_hi:[1,0]
	v_pk_mul_f32 v[34:35], v[34:35], v[50:51] op_sel_hi:[1,0]
	v_pk_mul_f32 v[36:37], v[36:37], v[50:51] op_sel_hi:[1,0]
	v_pk_mul_f32 v[38:39], v[38:39], v[50:51] op_sel_hi:[1,0]
	v_pk_mul_f32 v[40:41], v[40:41], v[50:51] op_sel_hi:[1,0]
	v_mul_f32_e32 v58, 0xbfb8aa3b, v46
	v_mul_f32_e32 v59, 0xbfb8aa3b, v47
	v_mul_f32_e32 v60, 0xbfb8aa3b, v48
	v_mul_f32_e32 v61, 0xbfb8aa3b, v49
	v_exp_f32_e32 v58, v58
	v_exp_f32_e32 v59, v59
	v_exp_f32_e32 v60, v60
	v_exp_f32_e32 v61, v61
	v_add_f32_e32 v58, 1.0, v58
	v_add_f32_e32 v59, 1.0, v59
	v_add_f32_e32 v60, 1.0, v60
	v_add_f32_e32 v61, 1.0, v61
	v_rcp_f32_e32 v58, v58
	v_rcp_f32_e32 v59, v59
	v_rcp_f32_e32 v60, v60
	v_rcp_f32_e32 v61, v61
	v_mul_f32_e32 v46, v46, v58
	v_mul_f32_e32 v47, v47, v59
	v_mul_f32_e32 v48, v48, v60
	v_mul_f32_e32 v49, v49, v61
	v_mul_f32_e32 v42, v42, v46
	v_mul_f32_e32 v43, v43, v47
	v_mul_f32_e32 v44, v44, v48
	v_mul_f32_e32 v45, v45, v49
	v_mul_f32_e32 v46, 0xbfb8aa3b, v38
	v_mul_f32_e32 v47, 0xbfb8aa3b, v39
	v_mul_f32_e32 v48, 0xbfb8aa3b, v40
	v_mul_f32_e32 v49, 0xbfb8aa3b, v41
	v_exp_f32_e32 v46, v46
	v_exp_f32_e32 v47, v47
	v_exp_f32_e32 v48, v48
	v_exp_f32_e32 v49, v49
	v_add_f32_e32 v46, 1.0, v46
	v_add_f32_e32 v47, 1.0, v47
	v_add_f32_e32 v48, 1.0, v48
	v_add_f32_e32 v49, 1.0, v49
	v_rcp_f32_e32 v46, v46
	v_rcp_f32_e32 v47, v47
	v_rcp_f32_e32 v48, v48
	v_rcp_f32_e32 v49, v49
	v_mul_f32_e32 v38, v38, v46
	v_mul_f32_e32 v39, v39, v47
	v_mul_f32_e32 v40, v40, v48
	v_mul_f32_e32 v41, v41, v49
	v_mul_f32_e32 v34, v34, v38
	v_mul_f32_e32 v35, v35, v39
	v_mul_f32_e32 v36, v36, v40
	v_mul_f32_e32 v37, v37, v41
	v_cvt_pk_bf16_f32 v38, v42, v43
	v_cvt_pk_bf16_f32 v39, v44, v45
	v_cvt_pk_bf16_f32 v40, v34, v35
	v_cvt_pk_bf16_f32 v41, v36, v37
	v_mad_i64_i32 v[46:47], s[4:5], v153, s6, v[114:115]
	v_lshl_add_u64 v[46:47], v[46:47], 0, v[116:117]
	flat_store_dwordx4 v[46:47], v[38:41] nt
	s_nop 1
	v_fmamk_f32 v34, v152, 0x3a000000, v224
	v_cmp_gt_f32_e32 vcc, s19, v34
	v_mul_f32_e32 v35, 0x4b800000, v34
	s_nop 0
	v_cndmask_b32_e32 v34, v34, v35, vcc
	v_rsq_f32_e32 v34, v34
	s_nop 0
	v_mul_f32_e32 v35, 0x45800000, v34
	v_cndmask_b32_e32 v34, v34, v35, vcc
	v_pk_mul_f32 v[26:27], v[26:27], v[34:35] op_sel_hi:[1,0]
	v_pk_mul_f32 v[28:29], v[28:29], v[34:35] op_sel_hi:[1,0]
	v_pk_mul_f32 v[30:31], v[30:31], v[34:35] op_sel_hi:[1,0]
	v_pk_mul_f32 v[32:33], v[32:33], v[34:35] op_sel_hi:[1,0]
	v_pk_mul_f32 v[18:19], v[18:19], v[34:35] op_sel_hi:[1,0]
	v_pk_mul_f32 v[20:21], v[20:21], v[34:35] op_sel_hi:[1,0]
	v_pk_mul_f32 v[22:23], v[22:23], v[34:35] op_sel_hi:[1,0]
	v_pk_mul_f32 v[24:25], v[24:25], v[34:35] op_sel_hi:[1,0]
	v_mul_f32_e32 v42, 0xbfb8aa3b, v30
	v_mul_f32_e32 v43, 0xbfb8aa3b, v31
	v_mul_f32_e32 v44, 0xbfb8aa3b, v32
	v_mul_f32_e32 v45, 0xbfb8aa3b, v33
	v_exp_f32_e32 v42, v42
	v_exp_f32_e32 v43, v43
	v_exp_f32_e32 v44, v44
	v_exp_f32_e32 v45, v45
	v_add_f32_e32 v42, 1.0, v42
	v_add_f32_e32 v43, 1.0, v43
	v_add_f32_e32 v44, 1.0, v44
	v_add_f32_e32 v45, 1.0, v45
	v_rcp_f32_e32 v42, v42
	v_rcp_f32_e32 v43, v43
	v_rcp_f32_e32 v44, v44
	v_rcp_f32_e32 v45, v45
	v_mul_f32_e32 v30, v30, v42
	v_mul_f32_e32 v31, v31, v43
	v_mul_f32_e32 v32, v32, v44
	v_mul_f32_e32 v33, v33, v45
	v_mul_f32_e32 v26, v26, v30
	v_mul_f32_e32 v27, v27, v31
	v_mul_f32_e32 v28, v28, v32
	v_mul_f32_e32 v29, v29, v33
	v_mul_f32_e32 v30, 0xbfb8aa3b, v22
	v_mul_f32_e32 v31, 0xbfb8aa3b, v23
	v_mul_f32_e32 v32, 0xbfb8aa3b, v24
	v_mul_f32_e32 v33, 0xbfb8aa3b, v25
	v_exp_f32_e32 v30, v30
	v_exp_f32_e32 v31, v31
	v_exp_f32_e32 v32, v32
	v_exp_f32_e32 v33, v33
	v_add_f32_e32 v30, 1.0, v30
	v_add_f32_e32 v31, 1.0, v31
	v_add_f32_e32 v32, 1.0, v32
	v_add_f32_e32 v33, 1.0, v33
	v_rcp_f32_e32 v30, v30
	v_rcp_f32_e32 v31, v31
	v_rcp_f32_e32 v32, v32
	v_rcp_f32_e32 v33, v33
	v_mul_f32_e32 v22, v22, v30
	v_mul_f32_e32 v23, v23, v31
	v_mul_f32_e32 v24, v24, v32
	v_mul_f32_e32 v25, v25, v33
	v_mul_f32_e32 v18, v18, v22
	v_mul_f32_e32 v19, v19, v23
	v_mul_f32_e32 v20, v20, v24
	v_mul_f32_e32 v21, v21, v25
	v_cvt_pk_bf16_f32 v22, v26, v27
	v_cvt_pk_bf16_f32 v23, v28, v29
	v_cvt_pk_bf16_f32 v24, v18, v19
	v_cvt_pk_bf16_f32 v25, v20, v21
	v_mad_i64_i32 v[30:31], s[4:5], v151, s6, v[114:115]
	v_lshl_add_u64 v[30:31], v[30:31], 0, v[116:117]
	flat_store_dwordx4 v[30:31], v[22:25] nt
	s_nop 1
	v_fmamk_f32 v18, v150, 0x3a000000, v224
	v_cmp_gt_f32_e32 vcc, s19, v18
	v_mul_f32_e32 v19, 0x4b800000, v18
	s_nop 0
	v_cndmask_b32_e32 v18, v18, v19, vcc
	v_rsq_f32_e32 v18, v18
	s_nop 0
	v_mul_f32_e32 v19, 0x45800000, v18
	v_cndmask_b32_e32 v18, v18, v19, vcc
	v_pk_mul_f32 v[10:11], v[10:11], v[18:19] op_sel_hi:[1,0]
	v_pk_mul_f32 v[12:13], v[12:13], v[18:19] op_sel_hi:[1,0]
	v_pk_mul_f32 v[14:15], v[14:15], v[18:19] op_sel_hi:[1,0]
	v_pk_mul_f32 v[16:17], v[16:17], v[18:19] op_sel_hi:[1,0]
	v_pk_mul_f32 v[2:3], v[2:3], v[18:19] op_sel_hi:[1,0]
	v_pk_mul_f32 v[4:5], v[4:5], v[18:19] op_sel_hi:[1,0]
	v_pk_mul_f32 v[6:7], v[6:7], v[18:19] op_sel_hi:[1,0]
	v_pk_mul_f32 v[8:9], v[8:9], v[18:19] op_sel_hi:[1,0]
	v_mul_f32_e32 v26, 0xbfb8aa3b, v14
	v_mul_f32_e32 v27, 0xbfb8aa3b, v15
	v_mul_f32_e32 v28, 0xbfb8aa3b, v16
	v_mul_f32_e32 v29, 0xbfb8aa3b, v17
	v_exp_f32_e32 v26, v26
	v_exp_f32_e32 v27, v27
	v_exp_f32_e32 v28, v28
	v_exp_f32_e32 v29, v29
	v_add_f32_e32 v26, 1.0, v26
	v_add_f32_e32 v27, 1.0, v27
	v_add_f32_e32 v28, 1.0, v28
	v_add_f32_e32 v29, 1.0, v29
	v_rcp_f32_e32 v26, v26
	v_rcp_f32_e32 v27, v27
	v_rcp_f32_e32 v28, v28
	v_rcp_f32_e32 v29, v29
	v_mul_f32_e32 v14, v14, v26
	v_mul_f32_e32 v15, v15, v27
	v_mul_f32_e32 v16, v16, v28
	v_mul_f32_e32 v17, v17, v29
	v_mul_f32_e32 v10, v10, v14
	v_mul_f32_e32 v11, v11, v15
	v_mul_f32_e32 v12, v12, v16
	v_mul_f32_e32 v13, v13, v17
	v_mul_f32_e32 v14, 0xbfb8aa3b, v6
	v_mul_f32_e32 v15, 0xbfb8aa3b, v7
	v_mul_f32_e32 v16, 0xbfb8aa3b, v8
	v_mul_f32_e32 v17, 0xbfb8aa3b, v9
	v_exp_f32_e32 v14, v14
	v_exp_f32_e32 v15, v15
	v_exp_f32_e32 v16, v16
	v_exp_f32_e32 v17, v17
	v_add_f32_e32 v14, 1.0, v14
	v_add_f32_e32 v15, 1.0, v15
	v_add_f32_e32 v16, 1.0, v16
	v_add_f32_e32 v17, 1.0, v17
	v_rcp_f32_e32 v14, v14
	v_rcp_f32_e32 v15, v15
	v_rcp_f32_e32 v16, v16
	v_rcp_f32_e32 v17, v17
	v_mul_f32_e32 v6, v6, v14
	v_mul_f32_e32 v7, v7, v15
	v_mul_f32_e32 v8, v8, v16
	v_mul_f32_e32 v9, v9, v17
	v_mul_f32_e32 v2, v2, v6
	v_mul_f32_e32 v3, v3, v7
	v_mul_f32_e32 v4, v4, v8
	v_mul_f32_e32 v5, v5, v9
	v_cvt_pk_bf16_f32 v6, v10, v11
	v_cvt_pk_bf16_f32 v7, v12, v13
	v_cvt_pk_bf16_f32 v8, v2, v3
	v_cvt_pk_bf16_f32 v9, v4, v5
	v_mad_i64_i32 v[14:15], s[4:5], v141, s6, v[114:115]
	v_lshl_add_u64 v[14:15], v[14:15], 0, v[116:117]
	s_mov_b64 s[4:5], -1
	s_andn2_b64 vcc, exec, s[40:41]
	flat_store_dwordx4 v[14:15], v[6:9] nt
	s_cbranch_vccnz .LBB0_1535
	s_andn2_b64 vcc, exec, s[42:43]
	s_cbranch_vccnz .LBB0_1534
	s_barrier
	s_branch .LBB0_1534
